# differential loop role A: K/V staging stores and next loads moved after the softmax, so both roles' LDS writes fall in the read-free tail of the interval
# speedup vs baseline: 1.0080x; 1.0034x over previous
; __device__ __forceinline__ s16x4 vtr(ldsp p) { return __builtin_bit_cast(s16x4, __builtin_amdgcn_ds_read_tr16_b64_v4i16((LAS v4i16_t*)p)); }
; template <bool DIFF>
; __device__ __forceinline__ void attn_unit(const AttnP& A, int b, int h, int qi, ldsp lds) {
;     ...
;             QK_BLOCK();
;             s16x4 vlo[8], vhi[8];
; #pragma unroll
;             for (int t = 0; t < 2; ++t)
; #pragma unroll
;                 for (int j = 0; j < 4; ++j) { vlo[t * 4 + j] = vtr(Vb + trb + (16 * j) * VP + t * 64); vhi[t * 4 + j] = vtr(Vb + trb + (16 * j + 8) * VP + t * 64); }
;             __builtin_amdgcn_sched_barrier(0);
;             MASK_BLOCK();
;             bool full = (kt == kt0);
;             float psa, psb;
;             if (!full) {
;                 EXPSUM_BLOCK();
;                 if (__any(psa + psb > 1.0e18f)) { full = true; QK_BLOCK();
;     ...
;             __builtin_amdgcn_s_setprio(1);
; #pragma unroll
;             for (int t = 0; t < 2; ++t)
; #pragma unroll
;                 for (int j = 0; j < 4; ++j) {
;                     const bf16x8 vf = (bf16x8){vlo[t * 4 + j][0], vlo[t * 4 + j][1], vlo[t * 4 + j][2], vlo[t * 4 + j][3], vhi[t * 4 + j][0], vhi[t * 4 + j][1], vhi[t * 4 + j][2], vhi[t * 4 + j][3]};
;                     o[t] = __builtin_amdgcn_mfma_f32_32x32x16_bf16(vf, pw[j], o[t], 0, 0, 0);
;                 }
;             if (DIFF) {
; #pragma unroll
;                 for (int t = 2; t < NTD; ++t)
; #pragma unroll
;                     for (int j = 0; j < 4; ++j) { vlo[(t - 2) * 4 + j] = vtr(Vb + trb + (16 * j) * VP + t * 64); vhi[(t - 2) * 4 + j] = vtr(Vb + trb + (16 * j + 8) * VP + t * 64); }
;                 __builtin_amdgcn_sched_barrier(0);
; #pragma unroll
;                 for (int t = 2; t < NTD; ++t)
; #pragma unroll
;                     for (int j = 0; j < 4; ++j) {
;                         const int i = (t - 2) * 4 + j;
;                         const bf16x8 vf = (bf16x8){vlo[i][0], vlo[i][1], vlo[i][2], vlo[i][3], vhi[i][0], vhi[i][1], vhi[i][2], vhi[i][3]};
;                         o[t] = __builtin_amdgcn_mfma_f32_32x32x16_bf16(vf, pw[j], o[t], 0, 0, 0);
;                     }
;             }
;             __builtin_amdgcn_s_setprio(0);
.Lda_s_even:
	ds_read_b64_tr_b16 v[148:149], v252 offset:17472
	ds_read_b64_tr_b16 v[150:151], v252 offset:20032
	ds_read_b64_tr_b16 v[152:153], v252 offset:17408
	ds_read_b64_tr_b16 v[154:155], v252 offset:19968
	ds_read_b64_tr_b16 v[156:157], v252 offset:22592
	ds_read_b64_tr_b16 v[158:159], v252 offset:25152
	ds_read_b64_tr_b16 v[160:161], v252 offset:22528
	ds_read_b64_tr_b16 v[162:163], v252 offset:25088
	ds_read_b64_tr_b16 v[164:165], v252 offset:27712
	ds_read_b64_tr_b16 v[166:167], v252 offset:30272
	ds_read_b64_tr_b16 v[168:169], v252 offset:27648
	ds_read_b64_tr_b16 v[170:171], v252 offset:30208
	ds_read_b64_tr_b16 v[172:173], v252 offset:32768
	ds_read_b64_tr_b16 v[174:175], v252 offset:35328
	ds_read_b64_tr_b16 v[176:177], v252 offset:32832
	ds_read_b64_tr_b16 v[178:179], v252 offset:35392
	s_waitcnt lgkmcnt(14)
	v_mfma_f32_32x32x16_bf16 v[34:49], v[148:151], v[98:101], v[34:49]
	ds_read_b64_tr_b16 v[90:91], v252 offset:17536
	ds_read_b64_tr_b16 v[92:93], v252 offset:20096
	s_waitcnt lgkmcnt(14)
	v_mfma_f32_32x32x16_bf16 v[50:65], v[152:155], v[98:101], v[50:65]
	ds_read_b64_tr_b16 v[94:95], v252 offset:17600
	ds_read_b64_tr_b16 v[96:97], v252 offset:20160
	s_waitcnt lgkmcnt(14)
	v_mfma_f32_32x32x16_bf16 v[34:49], v[156:159], v[102:105], v[34:49]
	ds_read_b64_tr_b16 v[106:107], v252 offset:22656
	ds_read_b64_tr_b16 v[108:109], v252 offset:25216
	s_waitcnt lgkmcnt(14)
	v_mfma_f32_32x32x16_bf16 v[50:65], v[160:163], v[102:105], v[50:65]
	ds_read_b64_tr_b16 v[110:111], v252 offset:22720
	ds_read_b64_tr_b16 v[112:113], v252 offset:25280
	s_waitcnt lgkmcnt(14)
	v_mfma_f32_32x32x16_bf16 v[34:49], v[164:167], v[82:85], v[34:49]
	ds_read_b64_tr_b16 v[240:241], v252 offset:27776
	ds_read_b64_tr_b16 v[242:243], v252 offset:30336
	s_waitcnt lgkmcnt(14)
	v_mfma_f32_32x32x16_bf16 v[50:65], v[168:171], v[82:85], v[50:65]
	ds_read_b64_tr_b16 v[148:149], v252 offset:27840
	ds_read_b64_tr_b16 v[150:151], v252 offset:30400
	s_waitcnt lgkmcnt(14)
	v_mfma_f32_32x32x16_bf16 v[50:65], v[172:175], v[86:89], v[50:65]
	ds_read_b64_tr_b16 v[152:153], v252 offset:32896
	ds_read_b64_tr_b16 v[154:155], v252 offset:35456
	s_waitcnt lgkmcnt(14)
	v_mfma_f32_32x32x16_bf16 v[34:49], v[176:179], v[86:89], v[34:49]
	ds_read_b64_tr_b16 v[156:157], v252 offset:32960
	ds_read_b64_tr_b16 v[158:159], v252 offset:35520
	s_waitcnt lgkmcnt(14)
	v_mfma_f32_32x32x16_bf16 v[18:33], v[90:93], v[98:101], v[18:33]
	ds_read_b128 v[160:163], v234
	s_waitcnt lgkmcnt(13)
	v_mfma_f32_32x32x16_bf16 v[2:17], v[94:97], v[98:101], v[2:17]
	ds_read_b128 v[164:167], v234 offset:8704
	s_waitcnt lgkmcnt(12)
	v_mfma_f32_32x32x16_bf16 v[18:33], v[106:109], v[102:105], v[18:33]
	ds_read_b128 v[168:171], v234 offset:32
	s_waitcnt lgkmcnt(11)
	v_mfma_f32_32x32x16_bf16 v[2:17], v[110:113], v[102:105], v[2:17]
	ds_read_b128 v[172:175], v234 offset:8736
	s_waitcnt lgkmcnt(10)
	v_mfma_f32_32x32x16_bf16 v[18:33], v[240:243], v[82:85], v[18:33]
	ds_read_b128 v[176:179], v234 offset:64
	s_waitcnt lgkmcnt(9)
	v_mfma_f32_32x32x16_bf16 v[2:17], v[148:151], v[82:85], v[2:17]
	ds_read_b128 v[240:243], v234 offset:8768
	s_waitcnt lgkmcnt(8)
	v_mfma_f32_32x32x16_bf16 v[18:33], v[152:155], v[86:89], v[18:33]
	ds_read_b128 v[148:151], v234 offset:96
	s_waitcnt lgkmcnt(7)
	v_mfma_f32_32x32x16_bf16 v[2:17], v[156:159], v[86:89], v[2:17]
	ds_read_b128 v[152:155], v234 offset:8800
	s_waitcnt lgkmcnt(7)
	v_mfma_f32_32x32x16_bf16 v[98:113], v[160:163], v[116:119], v[66:81]
	s_waitcnt lgkmcnt(6)
	v_mfma_f32_32x32x16_bf16 v[82:97], v[164:167], v[116:119], v[66:81]
	s_waitcnt lgkmcnt(5)
	v_mfma_f32_32x32x16_bf16 v[98:113], v[168:171], v[120:123], v[98:113]
	s_waitcnt lgkmcnt(4)
	v_mfma_f32_32x32x16_bf16 v[82:97], v[172:175], v[120:123], v[82:97]
	s_waitcnt lgkmcnt(3)
	v_mfma_f32_32x32x16_bf16 v[98:113], v[176:179], v[124:127], v[98:113]
	s_waitcnt lgkmcnt(2)
	v_mfma_f32_32x32x16_bf16 v[82:97], v[240:243], v[124:127], v[82:97]
	s_waitcnt lgkmcnt(1)
	v_mfma_f32_32x32x16_bf16 v[98:113], v[148:151], v[128:131], v[98:113]
	s_waitcnt lgkmcnt(0)
	v_mfma_f32_32x32x16_bf16 v[82:97], v[152:155], v[128:131], v[82:97]
	s_nop 7
	s_nop 3
	v_exp_f32_e32 v148, v98
	v_exp_f32_e32 v164, v82
	v_exp_f32_e32 v149, v99
	v_exp_f32_e32 v165, v83
	v_add_f32_e32 v237, 0, v148
	v_add_f32_e32 v238, 0, v164
	v_exp_f32_e32 v150, v100
	v_exp_f32_e32 v166, v84
	v_add_f32_e32 v237, v149, v237
	v_add_f32_e32 v238, v165, v238
	v_exp_f32_e32 v151, v101
	v_exp_f32_e32 v167, v85
	v_add_f32_e32 v237, v150, v237
	v_add_f32_e32 v238, v166, v238
	v_exp_f32_e32 v152, v102
	v_exp_f32_e32 v168, v86
	v_add_f32_e32 v237, v151, v237
	v_add_f32_e32 v238, v167, v238
	v_exp_f32_e32 v153, v103
	v_exp_f32_e32 v169, v87
	v_add_f32_e32 v237, v152, v237
	v_add_f32_e32 v238, v168, v238
	v_exp_f32_e32 v154, v104
	v_exp_f32_e32 v170, v88
	v_add_f32_e32 v237, v153, v237
	v_add_f32_e32 v238, v169, v238
	v_exp_f32_e32 v155, v105
	v_exp_f32_e32 v171, v89
	v_add_f32_e32 v237, v154, v237
	v_add_f32_e32 v238, v170, v238
	v_exp_f32_e32 v156, v106
	v_exp_f32_e32 v172, v90
	v_add_f32_e32 v237, v155, v237
	v_add_f32_e32 v238, v171, v238
	v_exp_f32_e32 v157, v107
	v_exp_f32_e32 v173, v91
	v_add_f32_e32 v237, v156, v237
	v_add_f32_e32 v238, v172, v238
	v_exp_f32_e32 v158, v108
	v_exp_f32_e32 v174, v92
	v_add_f32_e32 v237, v157, v237
	v_add_f32_e32 v238, v173, v238
	v_exp_f32_e32 v159, v109
	v_exp_f32_e32 v175, v93
	v_add_f32_e32 v237, v158, v237
	v_add_f32_e32 v238, v174, v238
	v_exp_f32_e32 v160, v110
	v_exp_f32_e32 v176, v94
	v_add_f32_e32 v237, v159, v237
	v_add_f32_e32 v238, v175, v238
	v_exp_f32_e32 v161, v111
	v_exp_f32_e32 v177, v95
	v_add_f32_e32 v237, v160, v237
	v_add_f32_e32 v238, v176, v238
	v_exp_f32_e32 v162, v112
	v_exp_f32_e32 v178, v96
	v_add_f32_e32 v237, v161, v237
	v_add_f32_e32 v238, v177, v238
	v_exp_f32_e32 v163, v113
	v_exp_f32_e32 v179, v97
	v_add_f32_e32 v237, v162, v237
	v_add_f32_e32 v238, v178, v238
	s_nop 0
	v_add_f32_e32 v237, v163, v237
	v_add_f32_e32 v238, v179, v238
	v_add_f32_e32 v204, v237, v238
	v_cmp_lt_f32_e32 vcc, s85, v204
	s_cbranch_vccnz .Lda_s_slow
; __device__ __forceinline__ unsigned cvtpk(float lo, float hi) { f32x2 v = {lo, hi}; bf16x2_t b = __builtin_convertvector(v, bf16x2_t); return __builtin_bit_cast(unsigned, b); }
; template <bool DIFF>
; __device__ __forceinline__ void attn_unit(const AttnP& A, int b, int h, int qi, ldsp lds) {
;     ...
;             l_run += psa + psb;
;     ...
;             bf16x8 pw[4];
; #pragma unroll
;             for (int j = 0; j < 4; ++j) {
;                 u32x4 pk;
;                 if (j < 2) { const int rb = 8 * (j & 1); pk.x = cvtpk(s0[rb], s0[rb + 1]); pk.y = cvtpk(s0[rb + 2], s0[rb + 3]); pk.z = cvtpk(s0[rb + 4], s0[rb + 5]); pk.w = cvtpk(s0[rb + 6], s0[rb + 7]); }
;                 else { const int rb = 8 * (j & 1); pk.x = cvtpk(s1[rb], s1[rb + 1]); pk.y = cvtpk(s1[rb + 2], s1[rb + 3]); pk.z = cvtpk(s1[rb + 4], s1[rb + 5]); pk.w = cvtpk(s1[rb + 6], s1[rb + 7]); }
;                 pw[j] = __builtin_bit_cast(bf16x8, pk);
;             }
;             __builtin_amdgcn_sched_barrier(0);
;             __builtin_amdgcn_s_setprio(1);
; #pragma unroll
;             for (int t = 0; t < 2; ++t)
; #pragma unroll
;                 for (int j = 0; j < 4; ++j) {
;                     const bf16x8 vf = (bf16x8){vlo[t * 4 + j][0], vlo[t * 4 + j][1], vlo[t * 4 + j][2], vlo[t * 4 + j][3], vhi[t * 4 + j][0], vhi[t * 4 + j][1], vhi[t * 4 + j][2], vhi[t * 4 + j][3]};
;                     o[t] = __builtin_amdgcn_mfma_f32_32x32x16_bf16(vf, pw[j], o[t], 0, 0, 0);
;                 }
;             if (DIFF) {
; #pragma unroll
;                 for (int t = 2; t < NTD; ++t)
; #pragma unroll
;                     for (int j = 0; j < 4; ++j) { vlo[(t - 2) * 4 + j] = vtr(Vb + trb + (16 * j) * VP + t * 64); vhi[(t - 2) * 4 + j] = vtr(Vb + trb + (16 * j + 8) * VP + t * 64); }
;                 __builtin_amdgcn_sched_barrier(0);
; #pragma unroll
;                 for (int t = 2; t < NTD; ++t)
; #pragma unroll
;                     for (int j = 0; j < 4; ++j) {
;                         const int i = (t - 2) * 4 + j;
;                         const bf16x8 vf = (bf16x8){vlo[i][0], vlo[i][1], vlo[i][2], vlo[i][3], vhi[i][0], vhi[i][1], vhi[i][2], vhi[i][3]};
;                         o[t] = __builtin_amdgcn_mfma_f32_32x32x16_bf16(vf, pw[j], o[t], 0, 0, 0);
;                     }
;             }
;             __builtin_amdgcn_s_setprio(0);
;         }
;         if (kt + 1 < nt) STORE_TILE((kt + 1) & 1);
	v_cvt_pk_bf16_f32 v98, v148, v149
	v_cvt_pk_bf16_f32 v99, v150, v151
	v_cvt_pk_bf16_f32 v100, v152, v153
	v_cvt_pk_bf16_f32 v101, v154, v155
	v_cvt_pk_bf16_f32 v102, v156, v157
	v_cvt_pk_bf16_f32 v103, v158, v159
	v_cvt_pk_bf16_f32 v104, v160, v161
	v_cvt_pk_bf16_f32 v105, v162, v163
	v_cvt_pk_bf16_f32 v82, v164, v165
	v_cvt_pk_bf16_f32 v83, v166, v167
	v_cvt_pk_bf16_f32 v84, v168, v169
	v_cvt_pk_bf16_f32 v85, v170, v171
	v_cvt_pk_bf16_f32 v86, v172, v173
	v_cvt_pk_bf16_f32 v87, v174, v175
	v_cvt_pk_bf16_f32 v88, v176, v177
	v_cvt_pk_bf16_f32 v89, v178, v179
	v_add_f32_e32 v230, v204, v230
	s_waitcnt vmcnt(0)
	ds_write_b128 v226, v[132:135] offset:38144
	ds_write_b128 v228, v[140:143] offset:38144
	ds_write_b128 v227, v[136:139] offset:17408
	ds_write_b128 v229, v[144:147] offset:17408
	global_load_dwordx4 v[136:139], v[196:197], off offset:2048
	global_load_dwordx4 v[144:147], v[198:199], off offset:2048
	v_lshl_add_u64 v[196:197], v[196:197], 0, s[26:27]
	v_lshl_add_u64 v[198:199], v[198:199], 0, s[26:27]
	global_load_dwordx4 v[132:135], v[196:197], off offset:1024
	global_load_dwordx4 v[140:143], v[198:199], off offset:1024
	s_waitcnt lgkmcnt(0)
	s_barrier
	s_add_i32 s75, s75, 1
	s_add_i32 s74, s74, 64
	s_cmp_gt_i32 s75, s23
	s_cbranch_scc1 .Lda_gen
.Lda_s_odd:
	ds_read_b64_tr_b16 v[148:149], v231 offset:17472
	ds_read_b64_tr_b16 v[150:151], v231 offset:20032
	ds_read_b64_tr_b16 v[152:153], v231 offset:17408
	ds_read_b64_tr_b16 v[154:155], v231 offset:19968
	ds_read_b64_tr_b16 v[156:157], v231 offset:22592
	ds_read_b64_tr_b16 v[158:159], v231 offset:25152
	ds_read_b64_tr_b16 v[160:161], v231 offset:22528
	ds_read_b64_tr_b16 v[162:163], v231 offset:25088
	ds_read_b64_tr_b16 v[164:165], v231 offset:27712
	ds_read_b64_tr_b16 v[166:167], v231 offset:30272
	ds_read_b64_tr_b16 v[168:169], v231 offset:27648
	ds_read_b64_tr_b16 v[170:171], v231 offset:30208
	ds_read_b64_tr_b16 v[172:173], v231 offset:32768
	ds_read_b64_tr_b16 v[174:175], v231 offset:35328
	ds_read_b64_tr_b16 v[176:177], v231 offset:32832
	ds_read_b64_tr_b16 v[178:179], v231 offset:35392
	s_waitcnt lgkmcnt(14)
	v_mfma_f32_32x32x16_bf16 v[34:49], v[148:151], v[98:101], v[34:49]
	ds_read_b64_tr_b16 v[90:91], v231 offset:17536
	ds_read_b64_tr_b16 v[92:93], v231 offset:20096
	s_waitcnt lgkmcnt(14)
	v_mfma_f32_32x32x16_bf16 v[50:65], v[152:155], v[98:101], v[50:65]
	ds_read_b64_tr_b16 v[94:95], v231 offset:17600
	ds_read_b64_tr_b16 v[96:97], v231 offset:20160
	s_waitcnt lgkmcnt(14)
	v_mfma_f32_32x32x16_bf16 v[34:49], v[156:159], v[102:105], v[34:49]
	ds_read_b64_tr_b16 v[106:107], v231 offset:22656
	ds_read_b64_tr_b16 v[108:109], v231 offset:25216
	s_waitcnt lgkmcnt(14)
	v_mfma_f32_32x32x16_bf16 v[50:65], v[160:163], v[102:105], v[50:65]
	ds_read_b64_tr_b16 v[110:111], v231 offset:22720
	ds_read_b64_tr_b16 v[112:113], v231 offset:25280
	s_waitcnt lgkmcnt(14)
	v_mfma_f32_32x32x16_bf16 v[34:49], v[164:167], v[82:85], v[34:49]
	ds_read_b64_tr_b16 v[240:241], v231 offset:27776
	ds_read_b64_tr_b16 v[242:243], v231 offset:30336
	s_waitcnt lgkmcnt(14)
	v_mfma_f32_32x32x16_bf16 v[50:65], v[168:171], v[82:85], v[50:65]
	ds_read_b64_tr_b16 v[148:149], v231 offset:27840
	ds_read_b64_tr_b16 v[150:151], v231 offset:30400
	s_waitcnt lgkmcnt(14)
	v_mfma_f32_32x32x16_bf16 v[50:65], v[172:175], v[86:89], v[50:65]
	ds_read_b64_tr_b16 v[152:153], v231 offset:32896
	ds_read_b64_tr_b16 v[154:155], v231 offset:35456
	s_waitcnt lgkmcnt(14)
	v_mfma_f32_32x32x16_bf16 v[34:49], v[176:179], v[86:89], v[34:49]
	ds_read_b64_tr_b16 v[156:157], v231 offset:32960
	ds_read_b64_tr_b16 v[158:159], v231 offset:35520
	s_waitcnt lgkmcnt(14)
	v_mfma_f32_32x32x16_bf16 v[18:33], v[90:93], v[98:101], v[18:33]
	ds_read_b128 v[160:163], v234 offset:38144
	s_waitcnt lgkmcnt(13)
	v_mfma_f32_32x32x16_bf16 v[2:17], v[94:97], v[98:101], v[2:17]
	ds_read_b128 v[164:167], v234 offset:46848
	s_waitcnt lgkmcnt(12)
	v_mfma_f32_32x32x16_bf16 v[18:33], v[106:109], v[102:105], v[18:33]
	ds_read_b128 v[168:171], v234 offset:38176
	s_waitcnt lgkmcnt(11)
	v_mfma_f32_32x32x16_bf16 v[2:17], v[110:113], v[102:105], v[2:17]
	ds_read_b128 v[172:175], v234 offset:46880
	s_waitcnt lgkmcnt(10)
	v_mfma_f32_32x32x16_bf16 v[18:33], v[240:243], v[82:85], v[18:33]
	ds_read_b128 v[176:179], v234 offset:38208
	s_waitcnt lgkmcnt(9)
; __device__ __forceinline__ s16x4 vtr(ldsp p) { return __builtin_bit_cast(s16x4, __builtin_amdgcn_ds_read_tr16_b64_v4i16((LAS v4i16_t*)p)); }
; template <bool DIFF>
; __device__ __forceinline__ void attn_unit(const AttnP& A, int b, int h, int qi, ldsp lds) {
;     ...
;             QK_BLOCK();
;             s16x4 vlo[8], vhi[8];
; #pragma unroll
;             for (int t = 0; t < 2; ++t)
; #pragma unroll
;                 for (int j = 0; j < 4; ++j) { vlo[t * 4 + j] = vtr(Vb + trb + (16 * j) * VP + t * 64); vhi[t * 4 + j] = vtr(Vb + trb + (16 * j + 8) * VP + t * 64); }
;             __builtin_amdgcn_sched_barrier(0);
;             MASK_BLOCK();
;             bool full = (kt == kt0);
;             float psa, psb;
;             if (!full) {
;                 EXPSUM_BLOCK();
;                 if (__any(psa + psb > 1.0e18f)) { full = true; QK_BLOCK();
; #pragma unroll
;                     for (int t = 0; t < 2; ++t)
; #pragma unroll
;                         for (int j = 0; j < 4; ++j) { vlo[t * 4 + j] = vtr(Vb + trb + (16 * j) * VP + t * 64); vhi[t * 4 + j] = vtr(Vb + trb + (16 * j + 8) * VP + t * 64); }
;                     MASK_BLOCK(); }
;             }
;             if (full) {
;                 float ma = fmaxf(fmaxf(s0[0], s0[1]), s1[0]), mb = fmaxf(fmaxf(s0[2], s0[3]), s1[1]);
;                 ma = fmaxf(fmaxf(ma, s1[2]), s1[3]);
; #pragma unroll
;                 for (int r = 4; r < 16; r += 4) { ma = fmaxf(fmaxf(ma, s0[r]), s0[r + 1]); mb = fmaxf(fmaxf(mb, s0[r + 2]), s0[r + 3]); ma = fmaxf(fmaxf(ma, s1[r]), s1[r + 1]); mb = fmaxf(fmaxf(mb, s1[r + 2]), s1[r + 3]); }
;                 const float rm = swap32_max(fmaxf(ma, mb));
;                 const float dl = (kt == kt0) ? ((rm == -INFINITY) ? 0.f : rm) : fmaxf(rm, 0.f);
;                 mhat += dl;
; #pragma unroll
;                 for (int r = 0; r < 16; ++r) { s0[r] -= dl; s1[r] -= dl; negm[r] = -mhat; }
;                 const float f = (kt == kt0) ? 1.0f : __builtin_amdgcn_exp2f(-dl);
;                 l_run *= f;
; #pragma unroll
;                 for (int t = 0; t < NTD; ++t)
; #pragma unroll
;                     for (int r = 0; r < 16; ++r) o[t][r] *= f;
;                 EXPSUM_BLOCK();
;             }
;             l_run += psa + psb;
;     ...
;             bf16x8 pw[4];
; #pragma unroll
;             for (int j = 0; j < 4; ++j) {
;                 u32x4 pk;
	v_mfma_f32_32x32x16_bf16 v[2:17], v[148:151], v[82:85], v[2:17]
	ds_read_b128 v[240:243], v234 offset:46912
	s_waitcnt lgkmcnt(8)
	v_mfma_f32_32x32x16_bf16 v[18:33], v[152:155], v[86:89], v[18:33]
	ds_read_b128 v[148:151], v234 offset:38240
	s_waitcnt lgkmcnt(7)
	v_mfma_f32_32x32x16_bf16 v[2:17], v[156:159], v[86:89], v[2:17]
	ds_read_b128 v[152:155], v234 offset:46944
	s_waitcnt lgkmcnt(7)
	v_mfma_f32_32x32x16_bf16 v[98:113], v[160:163], v[116:119], v[66:81]
	s_waitcnt lgkmcnt(6)
	v_mfma_f32_32x32x16_bf16 v[82:97], v[164:167], v[116:119], v[66:81]
	s_waitcnt lgkmcnt(5)
	v_mfma_f32_32x32x16_bf16 v[98:113], v[168:171], v[120:123], v[98:113]
	s_waitcnt lgkmcnt(4)
	v_mfma_f32_32x32x16_bf16 v[82:97], v[172:175], v[120:123], v[82:97]
	s_waitcnt lgkmcnt(3)
	v_mfma_f32_32x32x16_bf16 v[98:113], v[176:179], v[124:127], v[98:113]
	s_waitcnt lgkmcnt(2)
	v_mfma_f32_32x32x16_bf16 v[82:97], v[240:243], v[124:127], v[82:97]
	s_waitcnt lgkmcnt(1)
	v_mfma_f32_32x32x16_bf16 v[98:113], v[148:151], v[128:131], v[98:113]
	s_waitcnt lgkmcnt(0)
	v_mfma_f32_32x32x16_bf16 v[82:97], v[152:155], v[128:131], v[82:97]
	s_nop 7
	s_nop 3
	v_exp_f32_e32 v148, v98
	v_exp_f32_e32 v164, v82
	v_exp_f32_e32 v149, v99
	v_exp_f32_e32 v165, v83
	v_add_f32_e32 v237, 0, v148
	v_add_f32_e32 v238, 0, v164
	v_exp_f32_e32 v150, v100
	v_exp_f32_e32 v166, v84
	v_add_f32_e32 v237, v149, v237
	v_add_f32_e32 v238, v165, v238
	v_exp_f32_e32 v151, v101
	v_exp_f32_e32 v167, v85
	v_add_f32_e32 v237, v150, v237
	v_add_f32_e32 v238, v166, v238
	v_exp_f32_e32 v152, v102
	v_exp_f32_e32 v168, v86
	v_add_f32_e32 v237, v151, v237
	v_add_f32_e32 v238, v167, v238
	v_exp_f32_e32 v153, v103
	v_exp_f32_e32 v169, v87
	v_add_f32_e32 v237, v152, v237
	v_add_f32_e32 v238, v168, v238
	v_exp_f32_e32 v154, v104
	v_exp_f32_e32 v170, v88
	v_add_f32_e32 v237, v153, v237
	v_add_f32_e32 v238, v169, v238
	v_exp_f32_e32 v155, v105
	v_exp_f32_e32 v171, v89
	v_add_f32_e32 v237, v154, v237
	v_add_f32_e32 v238, v170, v238
	v_exp_f32_e32 v156, v106
	v_exp_f32_e32 v172, v90
	v_add_f32_e32 v237, v155, v237
	v_add_f32_e32 v238, v171, v238
	v_exp_f32_e32 v157, v107
	v_exp_f32_e32 v173, v91
	v_add_f32_e32 v237, v156, v237
	v_add_f32_e32 v238, v172, v238
	v_exp_f32_e32 v158, v108
	v_exp_f32_e32 v174, v92
	v_add_f32_e32 v237, v157, v237
	v_add_f32_e32 v238, v173, v238
	v_exp_f32_e32 v159, v109
	v_exp_f32_e32 v175, v93
	v_add_f32_e32 v237, v158, v237
	v_add_f32_e32 v238, v174, v238
	v_exp_f32_e32 v160, v110
	v_exp_f32_e32 v176, v94
	v_add_f32_e32 v237, v159, v237
	v_add_f32_e32 v238, v175, v238
	v_exp_f32_e32 v161, v111
	v_exp_f32_e32 v177, v95
	v_add_f32_e32 v237, v160, v237
	v_add_f32_e32 v238, v176, v238
	v_exp_f32_e32 v162, v112
	v_exp_f32_e32 v178, v96
	v_add_f32_e32 v237, v161, v237
	v_add_f32_e32 v238, v177, v238
	v_exp_f32_e32 v163, v113
	v_exp_f32_e32 v179, v97
	v_add_f32_e32 v237, v162, v237
	v_add_f32_e32 v238, v178, v238
	s_nop 0
	v_add_f32_e32 v237, v163, v237
	v_add_f32_e32 v238, v179, v238
	v_add_f32_e32 v204, v237, v238
	v_cmp_lt_f32_e32 vcc, s85, v204
	s_cbranch_vccnz .Lda_s_slow
	v_cvt_pk_bf16_f32 v98, v148, v149
	v_cvt_pk_bf16_f32 v99, v150, v151
	v_cvt_pk_bf16_f32 v100, v152, v153
	v_cvt_pk_bf16_f32 v101, v154, v155
	v_cvt_pk_bf16_f32 v102, v156, v157
	v_cvt_pk_bf16_f32 v103, v158, v159
	v_cvt_pk_bf16_f32 v104, v160, v161
	v_cvt_pk_bf16_f32 v105, v162, v163
	v_cvt_pk_bf16_f32 v82, v164, v165
	v_cvt_pk_bf16_f32 v83, v166, v167
	v_cvt_pk_bf16_f32 v84, v168, v169
	v_cvt_pk_bf16_f32 v85, v170, v171
	v_cvt_pk_bf16_f32 v86, v172, v173
	v_cvt_pk_bf16_f32 v87, v174, v175
	v_cvt_pk_bf16_f32 v88, v176, v177
	v_cvt_pk_bf16_f32 v89, v178, v179
	v_add_f32_e32 v230, v204, v230
	s_waitcnt vmcnt(0)
	ds_write_b128 v226, v[132:135]
	ds_write_b128 v228, v[140:143]
	ds_write_b128 v227, v[136:139] offset:55552
	ds_write_b128 v229, v[144:147] offset:55552
	global_load_dwordx4 v[136:139], v[196:197], off offset:2048
	global_load_dwordx4 v[144:147], v[198:199], off offset:2048
	v_lshl_add_u64 v[196:197], v[196:197], 0, s[26:27]
	v_lshl_add_u64 v[198:199], v[198:199], 0, s[26:27]
	global_load_dwordx4 v[132:135], v[196:197], off offset:1024
	global_load_dwordx4 v[140:143], v[198:199], off offset:1024
	s_waitcnt lgkmcnt(0)
	s_barrier
	s_add_i32 s75, s75, 1
	s_add_i32 s74, s74, 64
	s_cmp_le_i32 s75, s23
	s_cbranch_scc1 .Lda_s_even

; template <bool DIFF>
; __device__ __forceinline__ void attn_unit(const AttnP& A, int b, int h, int qi, ldsp lds) {
;     ...
;             }
;             __builtin_amdgcn_s_setprio(0);
;         }
;         if (kt + 1 < nt) STORE_TILE((kt + 1) & 1);
;         __syncthreads();
.Lda_s_slow:
	s_bitcmp1_b32 s75, 0
	s_cselect_b32 s45, 0x9500, 0
	s_sub_i32 s71, 0x9500, s45
	s_waitcnt vmcnt(0)
	s_add_i32 s0, s75, 1
	s_cmp_ge_i32 s0, s31
	s_cbranch_scc1 .Lda11_snok
	v_add_u32_e32 v204, s71, v226
	ds_write_b128 v204, v[132:135]
	v_add_u32_e32 v205, s71, v228
	ds_write_b128 v205, v[140:143]
